# v14: v13 + cross-half row max via v_permlane32_swap instead of ds_bpermute round trip
# speedup vs baseline: 1.0019x; 1.0019x over previous
; #define LAS __attribute__((address_space(3)))
; __device__ __forceinline__ void phase_attn(const Frame& F, int l, bool last, int ai, int na) {
;     ...
;             const int kpos0 = wlo + t * 64, q0w = qb * 128 + (w & 3) * 32;
;             const bool win = (t < nwin) && !(kpos0 <= q0w + 65 && kpos0 >= q0w - 97);
;             if ((t < nwin) && (kpos0 > q0w + 159 || kpos0 < q0w - 191)) continue;
;             f32x16 sacc[2];
; #pragma unroll
;             for (int kt = 0; kt < 2; ++kt) {
; #pragma unroll
;                 for (int e = 0; e < 16; ++e) sacc[kt][e] = 0.f;
; #pragma unroll
;                 for (int s = 0; s < 8; ++s) { const f16x8 a = *(const LAS f16x8*)(lds + bo + AT_K + ((kt * 32 + r32) * 136 + s * 16 + hh * 8) * 2);
;                     sacc[kt] = __builtin_amdgcn_mfma_f32_32x32x16_f16(a, qf[s], sacc[kt], 0, 0, 0); } }
;             float mx = -1e30f;
; #pragma unroll
;             for (int kt = 0; kt < 2; ++kt)
; #pragma unroll
;                 for (int e = 0; e < 16; ++e) {
;                     if (win) { const int kp = kpos0 + kt * 32 + (e & 3) + 8 * (e >> 2) + 4 * hh; const int dd = kp - qpos; if (dd > 128 || dd < -128) sacc[kt][e] = -1e30f; }
;                     mx = fmaxf(mx, sacc[kt][e]); }
.LBB0_614:
	s_andn2_b64 vcc, exec, s[10:11]
	s_cbranch_vccnz .LBB0_618
	s_cmp_gt_i32 s41, s34
	s_cselect_b64 s[10:11], -1, 0
	s_cmp_lt_i32 s41, s35
	s_cselect_b64 s[42:43], -1, 0
	s_or_b64 s[10:11], s[10:11], s[42:43]
	s_and_b64 s[10:11], s[2:3], s[10:11]
	s_add_i32 s2, s40, 0
	v_add_u32_e32 v14, s2, v189
	s_mov_b32 s3, 0xf149f2ca
	ds_read_b128 v[2:5], v14
	ds_read_b128 v[6:9], v14 offset:8704
	ds_read_b128 v[10:13], v14 offset:32
	ds_read_b128 v[200:203], v14 offset:8736
	ds_read_b128 v[242:245], v14 offset:64
	ds_read_b128 v[246:249], v14 offset:8768
	s_waitcnt lgkmcnt(5)
	v_mfma_f32_32x32x16_f16 v[96:111], v[2:5], v[112:115], 0
	ds_read_b128 v[2:5], v14 offset:96
	s_waitcnt lgkmcnt(5)
	v_mfma_f32_32x32x16_f16 v[80:95], v[6:9], v[112:115], 0
	ds_read_b128 v[6:9], v14 offset:8800
	s_waitcnt lgkmcnt(5)
	v_mfma_f32_32x32x16_f16 v[96:111], v[10:13], v[116:119], v[96:111]
	ds_read_b128 v[10:13], v14 offset:128
	s_waitcnt lgkmcnt(5)
	v_mfma_f32_32x32x16_f16 v[80:95], v[200:203], v[116:119], v[80:95]
	ds_read_b128 v[200:203], v14 offset:8832
	s_waitcnt lgkmcnt(5)
	v_mfma_f32_32x32x16_f16 v[96:111], v[242:245], v[120:123], v[96:111]
	ds_read_b128 v[242:245], v14 offset:160
	s_waitcnt lgkmcnt(5)
	v_mfma_f32_32x32x16_f16 v[80:95], v[246:249], v[120:123], v[80:95]
	ds_read_b128 v[246:249], v14 offset:8864
	s_waitcnt lgkmcnt(5)
	v_mfma_f32_32x32x16_f16 v[96:111], v[2:5], v[124:127], v[96:111]
	ds_read_b128 v[2:5], v14 offset:192
	s_waitcnt lgkmcnt(5)
	v_mfma_f32_32x32x16_f16 v[80:95], v[6:9], v[124:127], v[80:95]
	ds_read_b128 v[6:9], v14 offset:8896
	s_waitcnt lgkmcnt(5)
	v_mfma_f32_32x32x16_f16 v[96:111], v[10:13], v[128:131], v[96:111]
	ds_read_b128 v[10:13], v14 offset:224
	s_waitcnt lgkmcnt(5)
	v_mfma_f32_32x32x16_f16 v[80:95], v[200:203], v[128:131], v[80:95]
	ds_read_b128 v[200:203], v14 offset:8928
	s_waitcnt lgkmcnt(5)
	v_mfma_f32_32x32x16_f16 v[96:111], v[242:245], v[132:135], v[96:111]
	s_waitcnt lgkmcnt(4)
	v_mfma_f32_32x32x16_f16 v[80:95], v[246:249], v[132:135], v[80:95]
	s_waitcnt lgkmcnt(3)
	v_mfma_f32_32x32x16_f16 v[96:111], v[2:5], v[136:139], v[96:111]
	s_waitcnt lgkmcnt(2)
	v_mfma_f32_32x32x16_f16 v[80:95], v[6:9], v[136:139], v[80:95]
	s_waitcnt lgkmcnt(1)
	v_mfma_f32_32x32x16_f16 v[96:111], v[10:13], v[140:143], v[96:111]
	s_waitcnt lgkmcnt(0)
	v_mfma_f32_32x32x16_f16 v[80:95], v[200:203], v[140:143], v[80:95]
	s_cmp_eq_u64 s[10:11], 0
	s_cbranch_scc1 .Lattn_nomask
	v_add_u32_e32 v0, s38, v229
	v_add_u32_e32 v6, 0xffffff82, v0
	v_add_u32_e32 v7, 0xffffff87, v0
	v_add_u32_e32 v8, 0xffffff88, v0
	v_add_u32_e32 v9, 0xffffff89, v0
	v_add_u32_e32 v10, 0xffffff8a, v0
	s_nop 3
	v_add_u32_e32 v2, 0xffffff7f, v0
	v_cmp_gt_u32_e32 vcc, s83, v2
	s_and_b64 vcc, s[10:11], vcc
	v_add_u32_e32 v3, 0xffffff80, v0
	v_cndmask_b32_e32 v2, v96, v241, vcc
	v_cmp_gt_u32_e32 vcc, s83, v3
	s_and_b64 vcc, s[10:11], vcc
	v_add_u32_e32 v5, 0xffffff81, v0
	v_cndmask_b32_e32 v3, v97, v241, vcc
	v_cmp_gt_u32_e32 vcc, s83, v5
	s_and_b64 vcc, s[10:11], vcc
	v_add_u32_e32 v11, 0xffffff8f, v0
	v_cndmask_b32_e32 v5, v98, v241, vcc
	v_cmp_gt_u32_e32 vcc, s83, v6
	s_and_b64 vcc, s[10:11], vcc
	v_add_u32_e32 v12, 0xffffff90, v0
	v_cndmask_b32_e32 v6, v99, v241, vcc
	v_cmp_gt_u32_e32 vcc, s83, v7
	s_and_b64 vcc, s[10:11], vcc
	v_add_u32_e32 v13, 0xffffff91, v0
	v_cndmask_b32_e32 v7, v100, v241, vcc
	v_cmp_gt_u32_e32 vcc, s83, v8
	s_and_b64 vcc, s[10:11], vcc
	v_add_u32_e32 v14, 0xffffff92, v0
	v_cndmask_b32_e32 v8, v101, v241, vcc
	v_cmp_gt_u32_e32 vcc, s83, v9
	s_and_b64 vcc, s[10:11], vcc
	v_add_u32_e32 v15, 0xffffff97, v0
	v_cndmask_b32_e32 v9, v102, v241, vcc
	v_cmp_gt_u32_e32 vcc, s83, v10
	s_and_b64 vcc, s[10:11], vcc
	v_add_u32_e32 v96, 0xffffff98, v0
	v_cndmask_b32_e32 v10, v103, v241, vcc
	v_cmp_gt_u32_e32 vcc, s83, v11
	s_and_b64 vcc, s[10:11], vcc
	v_add_u32_e32 v97, 0xffffff99, v0
	v_cndmask_b32_e32 v11, v104, v241, vcc
	v_cmp_gt_u32_e32 vcc, s83, v12
	s_and_b64 vcc, s[10:11], vcc
	v_add_u32_e32 v98, 0xffffff9a, v0
	v_cndmask_b32_e32 v12, v105, v241, vcc
	v_cmp_gt_u32_e32 vcc, s83, v13
	s_and_b64 vcc, s[10:11], vcc
	v_add_u32_e32 v99, 0xffffff9f, v0
	v_cndmask_b32_e32 v13, v106, v241, vcc
	v_cmp_gt_u32_e32 vcc, s83, v14
	s_and_b64 vcc, s[10:11], vcc
	v_max3_f32 v4, v2, s3, v3
	v_cndmask_b32_e32 v14, v107, v241, vcc
	v_cmp_gt_u32_e32 vcc, s83, v15
	s_and_b64 vcc, s[10:11], vcc
	v_max3_f32 v4, v4, v5, v6
	v_cndmask_b32_e32 v15, v108, v241, vcc
	v_cmp_gt_u32_e32 vcc, s83, v96
	s_and_b64 vcc, s[10:11], vcc
	v_max3_f32 v4, v4, v7, v8
	v_cndmask_b32_e32 v96, v109, v241, vcc
	v_cmp_gt_u32_e32 vcc, s83, v97
	s_and_b64 vcc, s[10:11], vcc
	v_max3_f32 v4, v4, v9, v10
	v_cndmask_b32_e32 v97, v110, v241, vcc
	v_cmp_gt_u32_e32 vcc, s83, v98
	s_and_b64 vcc, s[10:11], vcc
	v_max3_f32 v4, v4, v11, v12
	v_cndmask_b32_e32 v98, v111, v241, vcc
	v_cmp_gt_u32_e32 vcc, s83, v99
	s_and_b64 vcc, s[10:11], vcc
	v_add_u32_e32 v99, 0xffffffa0, v0
	v_cndmask_b32_e32 v80, v80, v241, vcc
	v_cmp_gt_u32_e32 vcc, s83, v99
	s_and_b64 vcc, s[10:11], vcc
	v_add_u32_e32 v99, 0xffffffa1, v0
	v_cndmask_b32_e32 v81, v81, v241, vcc
	v_cmp_gt_u32_e32 vcc, s83, v99
	s_and_b64 vcc, s[10:11], vcc
	v_add_u32_e32 v99, 0xffffffa2, v0
	v_cndmask_b32_e32 v82, v82, v241, vcc
	v_cmp_gt_u32_e32 vcc, s83, v99
	s_and_b64 vcc, s[10:11], vcc
	v_add_u32_e32 v99, 0xffffffa7, v0
; #define LAS __attribute__((address_space(3)))
; __device__ __forceinline__ void phase_attn(const Frame& F, int l, bool last, int ai, int na) {
;     ...
;             float mx = -1e30f;
; #pragma unroll
;             for (int kt = 0; kt < 2; ++kt)
; #pragma unroll
;                 for (int e = 0; e < 16; ++e) {
;                     if (win) { const int kp = kpos0 + kt * 32 + (e & 3) + 8 * (e >> 2) + 4 * hh; const int dd = kp - qpos; if (dd > 128 || dd < -128) sacc[kt][e] = -1e30f; }
;                     mx = fmaxf(mx, sacc[kt][e]); }
;             mx = fmaxf(mx, __shfl_xor(mx, 32));
;             const bool upd = mx > mrun + 8.0f;
;             const bool anyupd = __builtin_amdgcn_ballot_w64(upd) != 0ull;
;             const float mnew = upd ? mx : mrun;
;             float rs = 0.f;
; #pragma unroll
;             for (int kt = 0; kt < 2; ++kt)
; #pragma unroll
;                 for (int g4 = 0; g4 < 4; ++g4) { float pv4[4];
; #pragma unroll
;                     for (int e = 0; e < 4; ++e) { pv4[e] = __builtin_amdgcn_exp2f(sacc[kt][g4 * 4 + e] - mnew); rs += pv4[e]; }
;                     *(LAS u32x2*)(Pw + (r32 * 72 + kt * 32 + g4 * 8 + hh * 4) * 2) = (u32x2){pk_f16(pv4[0], pv4[1]), pk_f16(pv4[2], pv4[3])}; }
;             rs += __shfl_xor(rs, 32);
	v_cndmask_b32_e32 v83, v83, v241, vcc
	v_cmp_gt_u32_e32 vcc, s83, v99
	s_and_b64 vcc, s[10:11], vcc
	v_add_u32_e32 v99, 0xffffffa8, v0
	v_cndmask_b32_e32 v84, v84, v241, vcc
	v_cmp_gt_u32_e32 vcc, s83, v99
	s_and_b64 vcc, s[10:11], vcc
	v_add_u32_e32 v99, 0xffffffa9, v0
	v_cndmask_b32_e32 v85, v85, v241, vcc
	v_cmp_gt_u32_e32 vcc, s83, v99
	s_and_b64 vcc, s[10:11], vcc
	v_add_u32_e32 v99, 0xffffffaa, v0
	v_cndmask_b32_e32 v86, v86, v241, vcc
	v_cmp_gt_u32_e32 vcc, s83, v99
	s_and_b64 vcc, s[10:11], vcc
	v_add_u32_e32 v99, 0xffffffaf, v0
	v_cndmask_b32_e32 v87, v87, v241, vcc
	v_cmp_gt_u32_e32 vcc, s83, v99
	s_and_b64 vcc, s[10:11], vcc
	v_add_u32_e32 v99, 0xffffffb0, v0
	v_cndmask_b32_e32 v88, v88, v241, vcc
	v_cmp_gt_u32_e32 vcc, s83, v99
	s_and_b64 vcc, s[10:11], vcc
	v_add_u32_e32 v99, 0xffffffb1, v0
	v_cndmask_b32_e32 v89, v89, v241, vcc
	v_cmp_gt_u32_e32 vcc, s83, v99
	s_and_b64 vcc, s[10:11], vcc
	v_add_u32_e32 v99, 0xffffffb2, v0
	v_cndmask_b32_e32 v90, v90, v241, vcc
	v_cmp_gt_u32_e32 vcc, s83, v99
	v_max3_f32 v4, v4, v13, v14
	s_and_b64 vcc, s[10:11], vcc
	v_add_u32_e32 v99, 0xffffffb7, v0
	v_max3_f32 v4, v4, v15, v96
	v_cndmask_b32_e32 v91, v91, v241, vcc
	v_cmp_gt_u32_e32 vcc, s83, v99
	v_max3_f32 v4, v4, v97, v98
	s_and_b64 vcc, s[10:11], vcc
	v_add_u32_e32 v99, 0xffffffb8, v0
	v_max3_f32 v4, v4, v80, v81
	v_cndmask_b32_e32 v92, v92, v241, vcc
	v_cmp_gt_u32_e32 vcc, s83, v99
	v_max3_f32 v4, v4, v82, v83
	s_and_b64 vcc, s[10:11], vcc
	v_add_u32_e32 v99, 0xffffffb9, v0
	v_max3_f32 v4, v4, v84, v85
	v_cndmask_b32_e32 v93, v93, v241, vcc
	v_cmp_gt_u32_e32 vcc, s83, v99
	v_max3_f32 v4, v4, v86, v87
	s_and_b64 vcc, s[10:11], vcc
	v_add_u32_e32 v0, 0xffffffba, v0
	v_max3_f32 v4, v4, v88, v89
	v_cndmask_b32_e32 v94, v94, v241, vcc
	v_cmp_gt_u32_e32 vcc, s83, v0
	v_max3_f32 v4, v4, v90, v91
	s_and_b64 vcc, s[10:11], vcc
	v_max3_f32 v4, v4, v92, v93
	v_cndmask_b32_e32 v95, v95, v241, vcc
	v_max3_f32 v0, v4, v94, v95
	v_mov_b32_e32 v4, v0
	s_nop 1
	v_permlane32_swap_b32_e32 v0, v4
	v_max_f32_e32 v0, v0, v4
	v_add_f32_e32 v4, 0x41000000, v230
	v_cmp_gt_f32_e32 vcc, v0, v4
	s_nop 1
	v_cndmask_b32_e32 v0, v230, v0, vcc
	v_sub_f32_e32 v2, v2, v0
	v_exp_f32_e32 v2, v2
	v_sub_f32_e32 v3, v3, v0
	v_exp_f32_e32 v3, v3
	v_sub_f32_e32 v5, v5, v0
	v_sub_f32_e32 v6, v6, v0
	v_exp_f32_e32 v5, v5
	v_exp_f32_e32 v6, v6
	v_add_f32_e32 v4, 0, v2
	v_add_f32_e32 v4, v3, v4
	v_add_f32_e32 v4, v5, v4
	v_cvt_pk_f16_f32 v2, v2, v3
	v_cvt_pk_f16_f32 v3, v5, v6
	v_sub_f32_e32 v5, v7, v0
	v_add_f32_e32 v4, v6, v4
	v_exp_f32_e32 v5, v5
	v_sub_f32_e32 v6, v8, v0
	v_exp_f32_e32 v6, v6
	v_sub_f32_e32 v7, v9, v0
	v_exp_f32_e32 v7, v7
	v_sub_f32_e32 v8, v10, v0
	v_exp_f32_e32 v8, v8
	v_add_f32_e32 v4, v5, v4
	v_add_f32_e32 v4, v6, v4
	v_add_f32_e32 v4, v7, v4
	v_add_f32_e32 v9, v8, v4
	v_cvt_pk_f16_f32 v4, v5, v6
	v_cvt_pk_f16_f32 v5, v7, v8
	ds_write2_b64 v228, v[2:3], v[4:5] offset1:2
	v_sub_f32_e32 v2, v11, v0
	v_exp_f32_e32 v2, v2
	v_sub_f32_e32 v4, v12, v0
	v_exp_f32_e32 v4, v4
	v_sub_f32_e32 v5, v13, v0
	v_add_f32_e32 v3, v2, v9
	v_exp_f32_e32 v5, v5
	v_sub_f32_e32 v6, v14, v0
	v_add_f32_e32 v3, v4, v3
	v_exp_f32_e32 v6, v6
	v_cvt_pk_f16_f32 v2, v2, v4
	v_sub_f32_e32 v4, v15, v0
	v_exp_f32_e32 v4, v4
	v_add_f32_e32 v3, v5, v3
	v_add_f32_e32 v7, v6, v3
	v_cvt_pk_f16_f32 v3, v5, v6
	v_sub_f32_e32 v6, v96, v0
	v_add_f32_e32 v5, v4, v7
	v_exp_f32_e32 v6, v6
	v_sub_f32_e32 v7, v97, v0
	v_exp_f32_e32 v7, v7
	v_sub_f32_e32 v8, v98, v0
	v_exp_f32_e32 v8, v8
	v_add_f32_e32 v5, v6, v5
	v_add_f32_e32 v5, v7, v5
	v_cvt_pk_f16_f32 v4, v4, v6
	v_add_f32_e32 v9, v8, v5
	v_cvt_pk_f16_f32 v5, v7, v8
	ds_write2_b64 v228, v[2:3], v[4:5] offset0:4 offset1:6
	v_sub_f32_e32 v2, v80, v0
	v_exp_f32_e32 v2, v2
	v_sub_f32_e32 v4, v81, v0
	v_exp_f32_e32 v4, v4
	v_sub_f32_e32 v5, v82, v0
	v_add_f32_e32 v3, v2, v9
	v_exp_f32_e32 v5, v5
	v_sub_f32_e32 v6, v83, v0
	v_add_f32_e32 v3, v4, v3
	v_exp_f32_e32 v6, v6
	v_cvt_pk_f16_f32 v2, v2, v4
	v_sub_f32_e32 v4, v84, v0
	v_exp_f32_e32 v4, v4
	v_add_f32_e32 v3, v5, v3
	v_add_f32_e32 v7, v6, v3
	v_cvt_pk_f16_f32 v3, v5, v6
	v_sub_f32_e32 v6, v85, v0
	v_add_f32_e32 v5, v4, v7
	v_exp_f32_e32 v6, v6
	v_sub_f32_e32 v7, v86, v0
	v_exp_f32_e32 v7, v7
	v_sub_f32_e32 v8, v87, v0
	v_exp_f32_e32 v8, v8
	v_add_f32_e32 v5, v6, v5
	v_add_f32_e32 v5, v7, v5
	v_cvt_pk_f16_f32 v4, v4, v6
	v_add_f32_e32 v9, v8, v5
	v_cvt_pk_f16_f32 v5, v7, v8
	ds_write2_b64 v228, v[2:3], v[4:5] offset0:8 offset1:10
	v_sub_f32_e32 v2, v88, v0
	v_exp_f32_e32 v2, v2
	v_sub_f32_e32 v4, v89, v0
	v_exp_f32_e32 v4, v4
	v_sub_f32_e32 v5, v90, v0
	v_exp_f32_e32 v5, v5
	v_sub_f32_e32 v6, v91, v0
	v_exp_f32_e32 v6, v6
	v_add_f32_e32 v3, v2, v9
	v_add_f32_e32 v3, v4, v3
	v_add_f32_e32 v3, v5, v3
	v_cvt_pk_f16_f32 v4, v2, v4
	v_sub_f32_e32 v2, v92, v0
	v_add_f32_e32 v3, v6, v3
	v_cvt_pk_f16_f32 v5, v5, v6
	v_exp_f32_e32 v6, v2
	v_sub_f32_e32 v7, v94, v0
	v_exp_f32_e32 v7, v7
	v_sub_f32_e32 v8, v95, v0
	v_add_f32_e32 v2, v6, v3
	v_sub_f32_e32 v3, v93, v0
	v_exp_f32_e32 v3, v3
	v_exp_f32_e32 v8, v8
	v_add_f32_e32 v2, v3, v2
	v_add_f32_e32 v2, v7, v2
	v_add_f32_e32 v2, v8, v2
	v_cvt_pk_f16_f32 v6, v6, v3
	ds_bpermute_b32 v3, v232, v2
	v_cvt_pk_f16_f32 v7, v7, v8
	ds_write2_b64 v228, v[4:5], v[6:7] offset0:12 offset1:14
	s_cbranch_vccz .LBB0_617

; #define LAS __attribute__((address_space(3)))
; __device__ __forceinline__ void phase_attn(const Frame& F, int l, bool last, int ai, int na) {
;     ...
;             float mx = -1e30f;
; #pragma unroll
;             for (int kt = 0; kt < 2; ++kt)
; #pragma unroll
;                 for (int e = 0; e < 16; ++e) {
;                     if (win) { const int kp = kpos0 + kt * 32 + (e & 3) + 8 * (e >> 2) + 4 * hh; const int dd = kp - qpos; if (dd > 128 || dd < -128) sacc[kt][e] = -1e30f; }
;                     mx = fmaxf(mx, sacc[kt][e]); }
;             mx = fmaxf(mx, __shfl_xor(mx, 32));
;             const bool upd = mx > mrun + 8.0f;
;             const bool anyupd = __builtin_amdgcn_ballot_w64(upd) != 0ull;
;             const float mnew = upd ? mx : mrun;
;             float rs = 0.f;
; #pragma unroll
;             for (int kt = 0; kt < 2; ++kt)
; #pragma unroll
;                 for (int g4 = 0; g4 < 4; ++g4) { float pv4[4];
; #pragma unroll
;                     for (int e = 0; e < 4; ++e) { pv4[e] = __builtin_amdgcn_exp2f(sacc[kt][g4 * 4 + e] - mnew); rs += pv4[e]; }
;                     *(LAS u32x2*)(Pw + (r32 * 72 + kt * 32 + g4 * 8 + hh * 4) * 2) = (u32x2){pk_f16(pv4[0], pv4[1]), pk_f16(pv4[2], pv4[3])}; }
;             rs += __shfl_xor(rs, 32);
;             if (anyupd) { const float alpha = __builtin_amdgcn_exp2f(mrun - mnew); lrun *= alpha;
; #pragma unroll
;                 for (int dt = 0; dt < 4; ++dt)
; #pragma unroll
;                     for (int e = 0; e < 16; ++e) oacc[dt][e] *= alpha; }
.Lattn_nomask:
	s_nop 8
	v_max3_f32 v4, v96, s3, v97
	v_max3_f32 v4, v4, v98, v99
	v_max3_f32 v4, v4, v100, v101
	v_max3_f32 v4, v4, v102, v103
	v_max3_f32 v4, v4, v104, v105
	v_max3_f32 v4, v4, v106, v107
	v_max3_f32 v4, v4, v108, v109
	v_max3_f32 v4, v4, v110, v111
	v_max3_f32 v4, v4, v80, v81
	v_max3_f32 v4, v4, v82, v83
	v_max3_f32 v4, v4, v84, v85
	v_max3_f32 v4, v4, v86, v87
	v_max3_f32 v4, v4, v88, v89
	v_max3_f32 v4, v4, v90, v91
	v_max3_f32 v4, v4, v92, v93
	v_max3_f32 v0, v4, v94, v95
	v_mov_b32_e32 v4, v0
	s_nop 1
	v_permlane32_swap_b32_e32 v0, v4
	v_max_f32_e32 v0, v0, v4
	v_add_f32_e32 v4, 0x41000000, v230
	v_cmp_gt_f32_e32 vcc, v0, v4
	s_nop 1
	v_cndmask_b32_e32 v0, v230, v0, vcc
	v_add_u32_e32 v12, s12, v191
	v_add_u32_e32 v13, s2, v191
	v_mov_b32_e32 v14, 0
	s_nop 1
	s_cbranch_vccz .Lnm_norescale
	v_sub_f32_e32 v4, v230, v0
	v_exp_f32_e32 v4, v4
	s_nop 0
	v_pk_mul_f32 v[78:79], v[78:79], v[4:5] op_sel_hi:[1,0]
	v_pk_mul_f32 v[76:77], v[76:77], v[4:5] op_sel_hi:[1,0]
	v_pk_mul_f32 v[74:75], v[74:75], v[4:5] op_sel_hi:[1,0]
	v_pk_mul_f32 v[72:73], v[72:73], v[4:5] op_sel_hi:[1,0]
	v_pk_mul_f32 v[70:71], v[70:71], v[4:5] op_sel_hi:[1,0]
	v_pk_mul_f32 v[68:69], v[68:69], v[4:5] op_sel_hi:[1,0]
	v_pk_mul_f32 v[66:67], v[66:67], v[4:5] op_sel_hi:[1,0]
	v_pk_mul_f32 v[64:65], v[64:65], v[4:5] op_sel_hi:[1,0]
	v_pk_mul_f32 v[62:63], v[62:63], v[4:5] op_sel_hi:[1,0]
	v_pk_mul_f32 v[60:61], v[60:61], v[4:5] op_sel_hi:[1,0]
	v_pk_mul_f32 v[58:59], v[58:59], v[4:5] op_sel_hi:[1,0]
	v_pk_mul_f32 v[56:57], v[56:57], v[4:5] op_sel_hi:[1,0]
	v_pk_mul_f32 v[54:55], v[54:55], v[4:5] op_sel_hi:[1,0]
	v_pk_mul_f32 v[52:53], v[52:53], v[4:5] op_sel_hi:[1,0]
	v_pk_mul_f32 v[50:51], v[50:51], v[4:5] op_sel_hi:[1,0]
	v_pk_mul_f32 v[48:49], v[48:49], v[4:5] op_sel_hi:[1,0]
	v_pk_mul_f32 v[46:47], v[46:47], v[4:5] op_sel_hi:[1,0]
	v_pk_mul_f32 v[44:45], v[44:45], v[4:5] op_sel_hi:[1,0]
	v_pk_mul_f32 v[42:43], v[42:43], v[4:5] op_sel_hi:[1,0]
	v_pk_mul_f32 v[40:41], v[40:41], v[4:5] op_sel_hi:[1,0]
	v_pk_mul_f32 v[38:39], v[38:39], v[4:5] op_sel_hi:[1,0]
	v_pk_mul_f32 v[36:37], v[36:37], v[4:5] op_sel_hi:[1,0]
	v_pk_mul_f32 v[34:35], v[34:35], v[4:5] op_sel_hi:[1,0]
	v_pk_mul_f32 v[32:33], v[32:33], v[4:5] op_sel_hi:[1,0]
	v_pk_mul_f32 v[30:31], v[30:31], v[4:5] op_sel_hi:[1,0]
	v_pk_mul_f32 v[28:29], v[28:29], v[4:5] op_sel_hi:[1,0]
	v_pk_mul_f32 v[26:27], v[26:27], v[4:5] op_sel_hi:[1,0]
	v_pk_mul_f32 v[24:25], v[24:25], v[4:5] op_sel_hi:[1,0]
	v_pk_mul_f32 v[22:23], v[22:23], v[4:5] op_sel_hi:[1,0]
	v_pk_mul_f32 v[20:21], v[20:21], v[4:5] op_sel_hi:[1,0]
	v_pk_mul_f32 v[18:19], v[18:19], v[4:5] op_sel_hi:[1,0]
	v_pk_mul_f32 v[16:17], v[16:17], v[4:5] op_sel_hi:[1,0]
	v_mul_f32_e32 v171, v171, v4
